# diff attention: one-barrier offset of the two wave halves (MLA back to lockstep)
# speedup vs baseline: 1.0022x; 1.0022x over previous
.LBB0_106:
	v_mov_b32_e32 v14, v0
	v_mov_b32_e32 v15, v0
	s_waitcnt vmcnt(0) lgkmcnt(0)
	s_barrier
	v_mov_b32_e32 v1, v0
	v_mov_b32_e32 v2, v0
	v_mov_b32_e32 v3, v0
	v_mov_b32_e32 v4, v0
	v_mov_b32_e32 v5, v0
	v_mov_b32_e32 v6, v0
	v_mov_b32_e32 v7, v0
	v_mov_b32_e32 v8, v0
	v_mov_b32_e32 v9, v0
	v_mov_b32_e32 v10, v0
	v_mov_b32_e32 v11, v0
	v_mov_b32_e32 v12, v0
	v_mov_b32_e32 v13, v0
	s_lshl_b32 s30, s43, 12
	s_lshl_b32 s44, s48, 7
	v_mov_b64_e32 v[62:63], v[14:15]
	v_mov_b64_e32 v[46:47], v[14:15]
	v_mov_b64_e32 v[30:31], v[14:15]
	s_add_i32 s43, s30, 0xffffff80
	v_add_u32_e32 v153, s44, v171
	v_add_u32_e32 v155, s44, v172
	s_add_i32 s45, s46, 0x80
	s_mov_b32 s50, 2
	s_mov_b32 s51, 1
	s_mov_b32 s53, 0
	v_mov_b32_e32 v157, 0
	v_mov_b32_e32 v159, 0
	v_mov_b32_e32 v96, 0
	v_mov_b32_e32 v97, 0
	v_mov_b32_e32 v98, 0
	v_mov_b32_e32 v99, 0
	v_mov_b32_e32 v100, 0
	v_mov_b32_e32 v101, 0
	v_mov_b32_e32 v102, 0
	v_mov_b32_e32 v103, 0
	v_mov_b32_e32 v104, 0
	v_mov_b32_e32 v105, 0
	v_mov_b32_e32 v106, 0
	v_mov_b32_e32 v107, 0
	v_mov_b32_e32 v108, 0
	v_mov_b32_e32 v109, 0
	v_mov_b32_e32 v110, 0
	v_mov_b32_e32 v111, 0
	v_mov_b64_e32 v[60:61], v[12:13]
	v_mov_b64_e32 v[58:59], v[10:11]
	v_mov_b64_e32 v[56:57], v[8:9]
	v_mov_b64_e32 v[54:55], v[6:7]
	v_mov_b64_e32 v[52:53], v[4:5]
	v_mov_b64_e32 v[50:51], v[2:3]
	v_mov_b64_e32 v[48:49], v[0:1]
	v_mov_b64_e32 v[44:45], v[12:13]
	v_mov_b64_e32 v[42:43], v[10:11]
	v_mov_b64_e32 v[40:41], v[8:9]
	v_mov_b64_e32 v[38:39], v[6:7]
	v_mov_b64_e32 v[36:37], v[4:5]
	v_mov_b64_e32 v[34:35], v[2:3]
	v_mov_b64_e32 v[32:33], v[0:1]
	v_mov_b64_e32 v[28:29], v[12:13]
	v_mov_b64_e32 v[26:27], v[10:11]
	v_mov_b64_e32 v[24:25], v[8:9]
	v_mov_b64_e32 v[22:23], v[6:7]
	v_mov_b64_e32 v[20:21], v[4:5]
	v_mov_b64_e32 v[18:19], v[2:3]
	v_mov_b64_e32 v[16:17], v[0:1]
	s_mov_b32 s52, 0
	s_waitcnt vmcnt(0)
	s_mul_i32 s30, s53, 0x2400
	v_add_u32_e32 v242, s30, v173
	s_mul_i32 s30, s53, 0x4800
	v_add_u32_e32 v243, s30, v174
	v_readfirstlane_b32 s30, v191
	s_lshr_b32 s30, s30, 8
	s_cmp_eq_u32 s30, 0
	s_cbranch_scc0 .Latt_diffT_top
.LBB0_107:
.LBB0_116:
	ds_read_b128 v[112:115], v242 offset:0
	ds_read_b128 v[116:119], v242 offset:4608
	ds_read_b128 v[120:123], v242 offset:32
	ds_read_b128 v[124:127], v242 offset:4640
	s_cmp_eq_u32 s52, 0
	s_cbranch_scc1 .Latt_diffL_dmaend
	s_add_i32 s30, s52, 1
	s_cmp_ge_u32 s30, s21
	s_cselect_b64 s[46:47], -1, 0
	s_cbranch_scc1 .Latt_diffL_dmaend
	s_cmp_lt_u32 s52, 3
	s_cselect_b32 s48, s45, s43
	s_sub_i32 s48, s48, 64
	s_mul_i32 s55, s51, 0x2400
	s_add_i32 s56, s55, s41
	s_mov_b32 m0, s56
	v_lshl_add_u32 v244, s48, 12, v153
	global_load_lds_dwordx4 v244, s[18:19]
	s_ashr_i32 s49, s48, 31
	s_lshl_b64 s[30:31], s[48:49], 1
	s_add_i32 s55, s55, s56
	s_add_i32 m0, s55, 0x6c00
	s_add_u32 s30, s39, s30
	s_addc_u32 s31, s42, s31
	global_load_lds_dwordx4 v150, s[30:31]
	s_add_i32 m0, s55, 0x8c00
	s_and_b64 vcc, exec, s[14:15]
	global_load_lds_dwordx4 v148, s[30:31]
	s_cbranch_vccz .Latt_diffL_dmax
.Latt_diffL_dmaend:
	s_waitcnt lgkmcnt(3)
	v_mfma_f32_32x32x16_bf16 v[64:79], v[112:115], v[130:133], v[96:111]
	ds_read_b128 v[112:115], v242 offset:64
	s_waitcnt lgkmcnt(3)
	v_mfma_f32_32x32x16_bf16 v[80:95], v[116:119], v[130:133], v[96:111]
	ds_read_b128 v[116:119], v242 offset:4672
	s_waitcnt lgkmcnt(3)
	v_mfma_f32_32x32x16_bf16 v[64:79], v[120:123], v[134:137], v[64:79]
	ds_read_b128 v[120:123], v242 offset:96
	s_waitcnt lgkmcnt(3)
	v_mfma_f32_32x32x16_bf16 v[80:95], v[124:127], v[134:137], v[80:95]
	ds_read_b128 v[124:127], v242 offset:4704
	s_waitcnt lgkmcnt(3)
	v_mfma_f32_32x32x16_bf16 v[64:79], v[112:115], v[138:141], v[64:79]
	s_waitcnt lgkmcnt(2)
	v_mfma_f32_32x32x16_bf16 v[80:95], v[116:119], v[138:141], v[80:95]
	s_waitcnt lgkmcnt(1)
	v_mfma_f32_32x32x16_bf16 v[64:79], v[120:123], v[142:145], v[64:79]
	s_waitcnt lgkmcnt(0)
	v_mfma_f32_32x32x16_bf16 v[80:95], v[124:127], v[142:145], v[80:95]
	ds_read_b128 v[112:115], v243 offset:27648
	ds_read_b128 v[116:119], v243 offset:32256
	ds_read_b128 v[120:123], v243 offset:36864
	ds_read_b128 v[124:127], v243 offset:41472
	s_cmp_eq_u32 s52, 0
	s_cselect_b32 s31, 0xff7fffff, 0
	s_nop 4
	v_max3_f32 v226, v64, v65, v66
	v_max3_f32 v227, v67, v68, v69
	v_max3_f32 v226, v226, v70, v71
	v_max3_f32 v227, v227, v72, v73
	v_max3_f32 v226, v226, v74, v75
	v_max3_f32 v227, v227, v76, v77
	v_max3_f32 v226, v226, v78, v79
	v_max3_f32 v228, v80, v81, v82
	v_max3_f32 v229, v83, v84, v85
	v_max3_f32 v228, v228, v86, v87
	v_max3_f32 v229, v229, v88, v89
	v_max3_f32 v228, v228, v90, v91
	v_max3_f32 v229, v229, v92, v93
	v_max3_f32 v228, v228, v94, v95
	v_max3_f32 v226, v226, v227, v228
	v_max_f32_e32 v226, v226, v229
	v_cmp_lt_f32_e32 vcc, s58, v226
	s_cmp_eq_u32 s52, 0
	s_cbranch_scc1 .Latt_diffL_rare
	s_cbranch_vccnz .Latt_diffL_rare
.Latt_diffL_norescale:
	v_exp_f32_e32 v64, v64
	v_exp_f32_e32 v65, v65
	v_exp_f32_e32 v66, v66
	v_exp_f32_e32 v67, v67
	v_exp_f32_e32 v68, v68
	v_exp_f32_e32 v69, v69
	v_exp_f32_e32 v70, v70
	v_exp_f32_e32 v71, v71
	v_cvt_pk_bf16_f32 v218, v64, v65
	v_cvt_pk_bf16_f32 v219, v66, v67
	v_cvt_pk_bf16_f32 v220, v68, v69
	v_cvt_pk_bf16_f32 v221, v70, v71
	s_waitcnt lgkmcnt(3)
	s_nop 0
	v_mfma_f32_32x32x16_bf16 v[0:15], v[112:115], v[218:221], v[0:15]
	ds_read_b128 v[112:115], v243 offset:27680
	v_exp_f32_e32 v72, v72
	v_exp_f32_e32 v73, v73
	v_exp_f32_e32 v74, v74
	v_exp_f32_e32 v75, v75
	s_waitcnt lgkmcnt(3)
	v_mfma_f32_32x32x16_bf16 v[48:63], v[116:119], v[218:221], v[48:63]
	ds_read_b128 v[116:119], v243 offset:32288
	v_cvt_pk_bf16_f32 v222, v72, v73
	v_exp_f32_e32 v76, v76
	v_exp_f32_e32 v77, v77
	v_cvt_pk_bf16_f32 v223, v74, v75
	s_waitcnt lgkmcnt(3)
	v_mfma_f32_32x32x16_bf16 v[32:47], v[120:123], v[218:221], v[32:47]
	ds_read_b128 v[120:123], v243 offset:36896
	v_exp_f32_e32 v78, v78
	v_exp_f32_e32 v79, v79
	v_cvt_pk_bf16_f32 v224, v76, v77
	v_cvt_pk_bf16_f32 v225, v78, v79
	s_waitcnt lgkmcnt(3)
	v_mfma_f32_32x32x16_bf16 v[16:31], v[124:127], v[218:221], v[16:31]
	ds_read_b128 v[124:127], v243 offset:41504
	v_add_f32_e32 v226, v64, v68
	v_add_f32_e32 v227, v65, v69
	v_add_f32_e32 v228, v66, v70
	v_add_f32_e32 v229, v67, v71
	s_waitcnt lgkmcnt(3)
	v_mfma_f32_32x32x16_bf16 v[0:15], v[112:115], v[222:225], v[0:15]
	ds_read_b128 v[112:115], v243 offset:27712
	v_exp_f32_e32 v80, v80
	v_exp_f32_e32 v81, v81
	v_exp_f32_e32 v82, v82
	v_exp_f32_e32 v83, v83
	v_cvt_pk_bf16_f32 v218, v80, v81
	s_waitcnt lgkmcnt(3)
	v_mfma_f32_32x32x16_bf16 v[48:63], v[116:119], v[222:225], v[48:63]
	ds_read_b128 v[116:119], v243 offset:32320
	v_exp_f32_e32 v84, v84
	v_exp_f32_e32 v85, v85
	v_cvt_pk_bf16_f32 v219, v82, v83
	v_exp_f32_e32 v86, v86
	v_exp_f32_e32 v87, v87
	s_waitcnt lgkmcnt(3)
	v_mfma_f32_32x32x16_bf16 v[32:47], v[120:123], v[222:225], v[32:47]
	ds_read_b128 v[120:123], v243 offset:36928
	v_cvt_pk_bf16_f32 v220, v84, v85
	v_cvt_pk_bf16_f32 v221, v86, v87
	v_add_f32_e32 v226, v226, v72
	v_add_f32_e32 v227, v227, v73
	v_add_f32_e32 v228, v228, v74
	s_waitcnt lgkmcnt(3)
	v_mfma_f32_32x32x16_bf16 v[16:31], v[124:127], v[222:225], v[16:31]
	ds_read_b128 v[124:127], v243 offset:41536
	v_add_f32_e32 v229, v229, v75
	v_add_f32_e32 v226, v226, v76
	v_add_f32_e32 v227, v227, v77
	v_add_f32_e32 v228, v228, v78
	v_add_f32_e32 v229, v229, v79
	s_waitcnt lgkmcnt(3)
	v_mfma_f32_32x32x16_bf16 v[0:15], v[112:115], v[218:221], v[0:15]
	ds_read_b128 v[112:115], v243 offset:27744
	v_exp_f32_e32 v88, v88
	v_exp_f32_e32 v89, v89
	v_exp_f32_e32 v90, v90
	v_exp_f32_e32 v91, v91
	v_cvt_pk_bf16_f32 v222, v88, v89
	s_waitcnt lgkmcnt(3)
	v_mfma_f32_32x32x16_bf16 v[48:63], v[116:119], v[218:221], v[48:63]
	ds_read_b128 v[116:119], v243 offset:32352
	v_exp_f32_e32 v92, v92
	v_exp_f32_e32 v93, v93
	v_cvt_pk_bf16_f32 v223, v90, v91
	v_exp_f32_e32 v94, v94
	v_exp_f32_e32 v95, v95
	s_waitcnt lgkmcnt(3)
	v_mfma_f32_32x32x16_bf16 v[32:47], v[120:123], v[218:221], v[32:47]
	ds_read_b128 v[120:123], v243 offset:36960
	v_cvt_pk_bf16_f32 v224, v92, v93
	v_cvt_pk_bf16_f32 v225, v94, v95
	v_add_f32_e32 v226, v226, v80
	v_add_f32_e32 v227, v227, v81
	v_add_f32_e32 v228, v228, v82
	s_waitcnt lgkmcnt(3)
	v_mfma_f32_32x32x16_bf16 v[16:31], v[124:127], v[218:221], v[16:31]
	ds_read_b128 v[124:127], v243 offset:41568
	v_add_f32_e32 v229, v229, v83
	v_add_f32_e32 v226, v226, v84
	v_add_f32_e32 v227, v227, v85
	v_add_f32_e32 v228, v228, v86
	v_add_f32_e32 v229, v229, v87
	s_waitcnt lgkmcnt(3)
	v_mfma_f32_32x32x16_bf16 v[0:15], v[112:115], v[222:225], v[0:15]
	v_add_f32_e32 v226, v226, v88
	v_add_f32_e32 v227, v227, v89
	s_waitcnt lgkmcnt(2)
	v_mfma_f32_32x32x16_bf16 v[48:63], v[116:119], v[222:225], v[48:63]
	v_add_f32_e32 v228, v228, v90
	v_add_f32_e32 v229, v229, v91
	s_waitcnt lgkmcnt(1)
	v_mfma_f32_32x32x16_bf16 v[32:47], v[120:123], v[222:225], v[32:47]
	v_add_f32_e32 v226, v226, v92
	v_add_f32_e32 v227, v227, v93
	s_waitcnt lgkmcnt(0)
	v_mfma_f32_32x32x16_bf16 v[16:31], v[124:127], v[222:225], v[16:31]
	v_add_f32_e32 v228, v228, v94
	v_add_f32_e32 v229, v229, v95
	v_add_f32_e32 v226, v226, v227
	v_add_f32_e32 v228, v228, v229
	v_add_f32_e32 v226, v226, v228
	v_add_f32_e32 v157, v157, v226
	s_waitcnt vmcnt(0)
	s_add_i32 s30, s50, 1
	s_cmp_lg_u32 s50, 2
	s_cselect_b32 s46, s30, 0
	s_add_i32 s52, s52, 1
	s_add_i32 s43, s43, 64
	s_add_i32 s45, s45, 64
	s_mov_b32 s53, s51
	s_mov_b32 s51, s50
	s_mov_b32 s50, s46
	s_mul_i32 s30, s53, 0x2400
	v_add_u32_e32 v242, s30, v173
	s_mul_i32 s30, s53, 0x4800
	v_add_u32_e32 v243, s30, v174
	s_cmp_eq_u32 s21, s52
	s_waitcnt lgkmcnt(0)
	s_barrier
	s_cbranch_scc0 .LBB0_107
	s_barrier
	s_branch .LBB0_88

.Latt_diffT_norescale:
	v_exp_f32_e32 v64, v64
	v_exp_f32_e32 v65, v65
	v_exp_f32_e32 v66, v66
	v_exp_f32_e32 v67, v67
	v_exp_f32_e32 v68, v68
	v_exp_f32_e32 v69, v69
	v_exp_f32_e32 v70, v70
	v_exp_f32_e32 v71, v71
	v_cvt_pk_bf16_f32 v218, v64, v65
	v_cvt_pk_bf16_f32 v219, v66, v67
	v_cvt_pk_bf16_f32 v220, v68, v69
	v_cvt_pk_bf16_f32 v221, v70, v71
	s_waitcnt vmcnt(0)
	s_barrier
	s_add_i32 s30, s52, 2
	s_cmp_ge_u32 s30, s21
	s_cselect_b64 s[46:47], -1, 0
	s_cbranch_scc1 .Latt_diffT_dmaend
	s_cmp_lt_u32 s52, 2
	s_cselect_b32 s48, s45, s43
	s_mul_i32 s55, s50, 0x2400
	s_add_i32 s56, s55, s41
	s_mov_b32 m0, s56
	v_lshl_add_u32 v244, s48, 12, v153
	global_load_lds_dwordx4 v244, s[18:19]
	s_ashr_i32 s49, s48, 31
	s_lshl_b64 s[30:31], s[48:49], 1
	s_add_i32 s55, s55, s56
	s_add_i32 m0, s55, 0x6c00
	s_add_u32 s30, s39, s30
	s_addc_u32 s31, s42, s31
	global_load_lds_dwordx4 v150, s[30:31]
	s_add_i32 m0, s55, 0x8c00
	s_and_b64 vcc, exec, s[14:15]
	global_load_lds_dwordx4 v148, s[30:31]
	s_cbranch_vccz .Latt_diffT_dmax
.Latt_diffT_dmaend:
	s_waitcnt lgkmcnt(3)
	s_nop 0
	v_mfma_f32_32x32x16_bf16 v[0:15], v[112:115], v[218:221], v[0:15]
	ds_read_b128 v[112:115], v243 offset:27680
	v_exp_f32_e32 v72, v72
	v_exp_f32_e32 v73, v73
	v_exp_f32_e32 v74, v74
	v_exp_f32_e32 v75, v75
	s_waitcnt lgkmcnt(3)
	v_mfma_f32_32x32x16_bf16 v[48:63], v[116:119], v[218:221], v[48:63]
	ds_read_b128 v[116:119], v243 offset:32288
	v_cvt_pk_bf16_f32 v222, v72, v73
	v_exp_f32_e32 v76, v76
	v_exp_f32_e32 v77, v77
	v_cvt_pk_bf16_f32 v223, v74, v75
	s_waitcnt lgkmcnt(3)
	v_mfma_f32_32x32x16_bf16 v[32:47], v[120:123], v[218:221], v[32:47]
	ds_read_b128 v[120:123], v243 offset:36896
	v_exp_f32_e32 v78, v78
	v_exp_f32_e32 v79, v79
	v_cvt_pk_bf16_f32 v224, v76, v77
	v_cvt_pk_bf16_f32 v225, v78, v79
	s_waitcnt lgkmcnt(3)
	v_mfma_f32_32x32x16_bf16 v[16:31], v[124:127], v[218:221], v[16:31]
	ds_read_b128 v[124:127], v243 offset:41504
	v_add_f32_e32 v226, v64, v68
	v_add_f32_e32 v227, v65, v69
	v_add_f32_e32 v228, v66, v70
	v_add_f32_e32 v229, v67, v71
	s_waitcnt lgkmcnt(3)
	v_mfma_f32_32x32x16_bf16 v[0:15], v[112:115], v[222:225], v[0:15]
	ds_read_b128 v[112:115], v243 offset:27712
	v_exp_f32_e32 v80, v80
	v_exp_f32_e32 v81, v81
	v_exp_f32_e32 v82, v82
	v_exp_f32_e32 v83, v83
	v_cvt_pk_bf16_f32 v218, v80, v81
	s_waitcnt lgkmcnt(3)
	v_mfma_f32_32x32x16_bf16 v[48:63], v[116:119], v[222:225], v[48:63]
	ds_read_b128 v[116:119], v243 offset:32320
	v_exp_f32_e32 v84, v84
	v_exp_f32_e32 v85, v85
	v_cvt_pk_bf16_f32 v219, v82, v83
	v_exp_f32_e32 v86, v86
	v_exp_f32_e32 v87, v87
	s_waitcnt lgkmcnt(3)
	v_mfma_f32_32x32x16_bf16 v[32:47], v[120:123], v[222:225], v[32:47]
	ds_read_b128 v[120:123], v243 offset:36928
	v_cvt_pk_bf16_f32 v220, v84, v85
	v_cvt_pk_bf16_f32 v221, v86, v87
	v_add_f32_e32 v226, v226, v72
	v_add_f32_e32 v227, v227, v73
	v_add_f32_e32 v228, v228, v74
	s_waitcnt lgkmcnt(3)
	v_mfma_f32_32x32x16_bf16 v[16:31], v[124:127], v[222:225], v[16:31]
	ds_read_b128 v[124:127], v243 offset:41536
	v_add_f32_e32 v229, v229, v75
	v_add_f32_e32 v226, v226, v76
	v_add_f32_e32 v227, v227, v77
	v_add_f32_e32 v228, v228, v78
	v_add_f32_e32 v229, v229, v79
	s_waitcnt lgkmcnt(3)
	v_mfma_f32_32x32x16_bf16 v[0:15], v[112:115], v[218:221], v[0:15]
	ds_read_b128 v[112:115], v243 offset:27744
	v_exp_f32_e32 v88, v88
	v_exp_f32_e32 v89, v89
	v_exp_f32_e32 v90, v90
	v_exp_f32_e32 v91, v91
	v_cvt_pk_bf16_f32 v222, v88, v89
	s_waitcnt lgkmcnt(3)
	v_mfma_f32_32x32x16_bf16 v[48:63], v[116:119], v[218:221], v[48:63]
	ds_read_b128 v[116:119], v243 offset:32352
	v_exp_f32_e32 v92, v92
	v_exp_f32_e32 v93, v93
	v_cvt_pk_bf16_f32 v223, v90, v91
	v_exp_f32_e32 v94, v94
	v_exp_f32_e32 v95, v95
	s_waitcnt lgkmcnt(3)
	v_mfma_f32_32x32x16_bf16 v[32:47], v[120:123], v[218:221], v[32:47]
	ds_read_b128 v[120:123], v243 offset:36960
	v_cvt_pk_bf16_f32 v224, v92, v93
	v_cvt_pk_bf16_f32 v225, v94, v95
	v_add_f32_e32 v226, v226, v80
	v_add_f32_e32 v227, v227, v81
	v_add_f32_e32 v228, v228, v82
	s_waitcnt lgkmcnt(3)
	v_mfma_f32_32x32x16_bf16 v[16:31], v[124:127], v[218:221], v[16:31]
	ds_read_b128 v[124:127], v243 offset:41568
	v_add_f32_e32 v229, v229, v83
	v_add_f32_e32 v226, v226, v84
	v_add_f32_e32 v227, v227, v85
	v_add_f32_e32 v228, v228, v86
	v_add_f32_e32 v229, v229, v87
	s_waitcnt lgkmcnt(3)
	v_mfma_f32_32x32x16_bf16 v[0:15], v[112:115], v[222:225], v[0:15]
	v_add_f32_e32 v226, v226, v88
	v_add_f32_e32 v227, v227, v89
	s_waitcnt lgkmcnt(2)
	v_mfma_f32_32x32x16_bf16 v[48:63], v[116:119], v[222:225], v[48:63]
	v_add_f32_e32 v228, v228, v90
	v_add_f32_e32 v229, v229, v91
	s_waitcnt lgkmcnt(1)
	v_mfma_f32_32x32x16_bf16 v[32:47], v[120:123], v[222:225], v[32:47]
	v_add_f32_e32 v226, v226, v92
	v_add_f32_e32 v227, v227, v93
	s_waitcnt lgkmcnt(0)
	v_mfma_f32_32x32x16_bf16 v[16:31], v[124:127], v[222:225], v[16:31]
	v_add_f32_e32 v228, v228, v94
	v_add_f32_e32 v229, v229, v95
	v_add_f32_e32 v226, v226, v227
	v_add_f32_e32 v228, v228, v229
	v_add_f32_e32 v226, v226, v228
	v_add_f32_e32 v157, v157, v226
	s_add_i32 s30, s50, 1
	s_cmp_lg_u32 s50, 2
	s_cselect_b32 s46, s30, 0
	s_add_i32 s52, s52, 1
	s_add_i32 s43, s43, 64
	s_add_i32 s45, s45, 64
	s_mov_b32 s53, s51
	s_mov_b32 s51, s50
	s_mov_b32 s50, s46
	s_mul_i32 s30, s53, 0x2400
	v_add_u32_e32 v242, s30, v173
	s_mul_i32 s30, s53, 0x4800
	v_add_u32_e32 v243, s30, v174
	s_cmp_eq_u32 s21, s52
	s_cbranch_scc0 .Latt_diffT_top
	s_barrier
	s_branch .LBB0_88
.Latt_diffL_dmax:
	s_add_i32 m0, s55, 0xac00
	s_and_b64 vcc, exec, s[8:9]
	global_load_lds_dwordx4 v146, s[30:31]
	s_cbranch_vccnz .Latt_diffL_dmaend
	s_add_i32 m0, s56, 0x2000
	v_lshl_add_u32 v244, s48, 12, v155
	global_load_lds_dwordx4 v244, s[18:19]
	s_branch .Latt_diffL_dmaend
.Latt_diffT_dmax:
	s_add_i32 m0, s55, 0xac00
	s_and_b64 vcc, exec, s[8:9]
	global_load_lds_dwordx4 v146, s[30:31]
	s_cbranch_vccnz .Latt_diffT_dmaend
	s_add_i32 m0, s56, 0x2000
	v_lshl_add_u32 v244, s48, 12, v155
	global_load_lds_dwordx4 v244, s[18:19]
	s_branch .Latt_diffT_dmaend
.Latt_diffL_rare:
	v_mov_b32_e32 v227, v226
	s_nop 1
	v_permlane32_swap_b32_e32 v226, v227
	v_max_f32_e32 v237, v226, v227
	v_max_f32_e32 v238, s31, v237
	v_max_f32_e32 v239, 0, v238
	v_add_f32_e32 v159, v159, v238
	v_exp_f32_e64 v240, -v239
	v_sub_f32_e32 v96, v96, v238
	v_mov_b32_e32 v97, v96
	v_mov_b32_e32 v98, v96
	v_mov_b32_e32 v99, v96
	v_mov_b32_e32 v100, v96
	v_mov_b32_e32 v101, v96
	v_mov_b32_e32 v102, v96
	v_mov_b32_e32 v103, v96
	v_mov_b32_e32 v104, v96
	v_mov_b32_e32 v105, v96
	v_mov_b32_e32 v106, v96
	v_mov_b32_e32 v107, v96
	v_mov_b32_e32 v108, v96
	v_mov_b32_e32 v109, v96
	v_mov_b32_e32 v110, v96
	v_mov_b32_e32 v111, v96
	v_sub_f32_e32 v64, v64, v238
	v_sub_f32_e32 v65, v65, v238
	v_sub_f32_e32 v66, v66, v238
	v_sub_f32_e32 v67, v67, v238
	v_sub_f32_e32 v68, v68, v238
	v_sub_f32_e32 v69, v69, v238
	v_sub_f32_e32 v70, v70, v238
	v_sub_f32_e32 v71, v71, v238
	v_sub_f32_e32 v72, v72, v238
	v_sub_f32_e32 v73, v73, v238
	v_sub_f32_e32 v74, v74, v238
	v_sub_f32_e32 v75, v75, v238
	v_sub_f32_e32 v76, v76, v238
	v_sub_f32_e32 v77, v77, v238
	v_sub_f32_e32 v78, v78, v238
	v_sub_f32_e32 v79, v79, v238
	v_sub_f32_e32 v80, v80, v238
	v_sub_f32_e32 v81, v81, v238
	v_sub_f32_e32 v82, v82, v238
	v_sub_f32_e32 v83, v83, v238
	v_sub_f32_e32 v84, v84, v238
	v_sub_f32_e32 v85, v85, v238
	v_sub_f32_e32 v86, v86, v238
	v_sub_f32_e32 v87, v87, v238
	v_sub_f32_e32 v88, v88, v238
	v_sub_f32_e32 v89, v89, v238
	v_sub_f32_e32 v90, v90, v238
	v_sub_f32_e32 v91, v91, v238
	v_sub_f32_e32 v92, v92, v238
	v_sub_f32_e32 v93, v93, v238
	v_sub_f32_e32 v94, v94, v238
	v_sub_f32_e32 v95, v95, v238
	v_mul_f32_e32 v157, v157, v240
	v_pk_mul_f32 v[0:1], v[0:1], v[240:241] op_sel_hi:[1,0]
	v_pk_mul_f32 v[2:3], v[2:3], v[240:241] op_sel_hi:[1,0]
	v_pk_mul_f32 v[4:5], v[4:5], v[240:241] op_sel_hi:[1,0]
	v_pk_mul_f32 v[6:7], v[6:7], v[240:241] op_sel_hi:[1,0]
	v_pk_mul_f32 v[8:9], v[8:9], v[240:241] op_sel_hi:[1,0]
	v_pk_mul_f32 v[10:11], v[10:11], v[240:241] op_sel_hi:[1,0]
	v_pk_mul_f32 v[12:13], v[12:13], v[240:241] op_sel_hi:[1,0]
	v_pk_mul_f32 v[14:15], v[14:15], v[240:241] op_sel_hi:[1,0]
	v_pk_mul_f32 v[48:49], v[48:49], v[240:241] op_sel_hi:[1,0]
	v_pk_mul_f32 v[50:51], v[50:51], v[240:241] op_sel_hi:[1,0]
	v_pk_mul_f32 v[52:53], v[52:53], v[240:241] op_sel_hi:[1,0]
	v_pk_mul_f32 v[54:55], v[54:55], v[240:241] op_sel_hi:[1,0]
	v_pk_mul_f32 v[56:57], v[56:57], v[240:241] op_sel_hi:[1,0]
	v_pk_mul_f32 v[58:59], v[58:59], v[240:241] op_sel_hi:[1,0]
	v_pk_mul_f32 v[60:61], v[60:61], v[240:241] op_sel_hi:[1,0]
	v_pk_mul_f32 v[62:63], v[62:63], v[240:241] op_sel_hi:[1,0]
	v_pk_mul_f32 v[32:33], v[32:33], v[240:241] op_sel_hi:[1,0]
	v_pk_mul_f32 v[34:35], v[34:35], v[240:241] op_sel_hi:[1,0]
	v_pk_mul_f32 v[36:37], v[36:37], v[240:241] op_sel_hi:[1,0]
	v_pk_mul_f32 v[38:39], v[38:39], v[240:241] op_sel_hi:[1,0]
	v_pk_mul_f32 v[40:41], v[40:41], v[240:241] op_sel_hi:[1,0]
	v_pk_mul_f32 v[42:43], v[42:43], v[240:241] op_sel_hi:[1,0]
	v_pk_mul_f32 v[44:45], v[44:45], v[240:241] op_sel_hi:[1,0]
	v_pk_mul_f32 v[46:47], v[46:47], v[240:241] op_sel_hi:[1,0]
	v_pk_mul_f32 v[16:17], v[16:17], v[240:241] op_sel_hi:[1,0]
	v_pk_mul_f32 v[18:19], v[18:19], v[240:241] op_sel_hi:[1,0]
	v_pk_mul_f32 v[20:21], v[20:21], v[240:241] op_sel_hi:[1,0]
	v_pk_mul_f32 v[22:23], v[22:23], v[240:241] op_sel_hi:[1,0]
	v_pk_mul_f32 v[24:25], v[24:25], v[240:241] op_sel_hi:[1,0]
	v_pk_mul_f32 v[26:27], v[26:27], v[240:241] op_sel_hi:[1,0]
	v_pk_mul_f32 v[28:29], v[28:29], v[240:241] op_sel_hi:[1,0]
	v_pk_mul_f32 v[30:31], v[30:31], v[240:241] op_sel_hi:[1,0]
	s_branch .Latt_diffL_norescale
.Latt_diffT_rare:
	v_mov_b32_e32 v227, v226
	s_nop 1
	v_permlane32_swap_b32_e32 v226, v227
	v_max_f32_e32 v237, v226, v227
	v_max_f32_e32 v238, s31, v237
	v_max_f32_e32 v239, 0, v238
	v_add_f32_e32 v159, v159, v238
	v_exp_f32_e64 v240, -v239
	v_sub_f32_e32 v96, v96, v238
	v_mov_b32_e32 v97, v96
	v_mov_b32_e32 v98, v96
	v_mov_b32_e32 v99, v96
	v_mov_b32_e32 v100, v96
	v_mov_b32_e32 v101, v96
	v_mov_b32_e32 v102, v96
	v_mov_b32_e32 v103, v96
	v_mov_b32_e32 v104, v96
	v_mov_b32_e32 v105, v96
	v_mov_b32_e32 v106, v96
	v_mov_b32_e32 v107, v96
	v_mov_b32_e32 v108, v96
	v_mov_b32_e32 v109, v96
	v_mov_b32_e32 v110, v96
	v_mov_b32_e32 v111, v96
	v_sub_f32_e32 v64, v64, v238
	v_sub_f32_e32 v65, v65, v238
	v_sub_f32_e32 v66, v66, v238
	v_sub_f32_e32 v67, v67, v238
	v_sub_f32_e32 v68, v68, v238
	v_sub_f32_e32 v69, v69, v238
	v_sub_f32_e32 v70, v70, v238
	v_sub_f32_e32 v71, v71, v238
	v_sub_f32_e32 v72, v72, v238
	v_sub_f32_e32 v73, v73, v238
	v_sub_f32_e32 v74, v74, v238
	v_sub_f32_e32 v75, v75, v238
	v_sub_f32_e32 v76, v76, v238
	v_sub_f32_e32 v77, v77, v238
	v_sub_f32_e32 v78, v78, v238
	v_sub_f32_e32 v79, v79, v238
	v_sub_f32_e32 v80, v80, v238
	v_sub_f32_e32 v81, v81, v238
	v_sub_f32_e32 v82, v82, v238
	v_sub_f32_e32 v83, v83, v238
	v_sub_f32_e32 v84, v84, v238
	v_sub_f32_e32 v85, v85, v238
	v_sub_f32_e32 v86, v86, v238
	v_sub_f32_e32 v87, v87, v238
	v_sub_f32_e32 v88, v88, v238
	v_sub_f32_e32 v89, v89, v238
	v_sub_f32_e32 v90, v90, v238
	v_sub_f32_e32 v91, v91, v238
	v_sub_f32_e32 v92, v92, v238
	v_sub_f32_e32 v93, v93, v238
	v_sub_f32_e32 v94, v94, v238
	v_sub_f32_e32 v95, v95, v238
	v_mul_f32_e32 v157, v157, v240
	v_pk_mul_f32 v[0:1], v[0:1], v[240:241] op_sel_hi:[1,0]
	v_pk_mul_f32 v[2:3], v[2:3], v[240:241] op_sel_hi:[1,0]
	v_pk_mul_f32 v[4:5], v[4:5], v[240:241] op_sel_hi:[1,0]
	v_pk_mul_f32 v[6:7], v[6:7], v[240:241] op_sel_hi:[1,0]
	v_pk_mul_f32 v[8:9], v[8:9], v[240:241] op_sel_hi:[1,0]
	v_pk_mul_f32 v[10:11], v[10:11], v[240:241] op_sel_hi:[1,0]
	v_pk_mul_f32 v[12:13], v[12:13], v[240:241] op_sel_hi:[1,0]
	v_pk_mul_f32 v[14:15], v[14:15], v[240:241] op_sel_hi:[1,0]
	v_pk_mul_f32 v[48:49], v[48:49], v[240:241] op_sel_hi:[1,0]
	v_pk_mul_f32 v[50:51], v[50:51], v[240:241] op_sel_hi:[1,0]
	v_pk_mul_f32 v[52:53], v[52:53], v[240:241] op_sel_hi:[1,0]
	v_pk_mul_f32 v[54:55], v[54:55], v[240:241] op_sel_hi:[1,0]
	v_pk_mul_f32 v[56:57], v[56:57], v[240:241] op_sel_hi:[1,0]
	v_pk_mul_f32 v[58:59], v[58:59], v[240:241] op_sel_hi:[1,0]
	v_pk_mul_f32 v[60:61], v[60:61], v[240:241] op_sel_hi:[1,0]
	v_pk_mul_f32 v[62:63], v[62:63], v[240:241] op_sel_hi:[1,0]
	v_pk_mul_f32 v[32:33], v[32:33], v[240:241] op_sel_hi:[1,0]
	v_pk_mul_f32 v[34:35], v[34:35], v[240:241] op_sel_hi:[1,0]
	v_pk_mul_f32 v[36:37], v[36:37], v[240:241] op_sel_hi:[1,0]
	v_pk_mul_f32 v[38:39], v[38:39], v[240:241] op_sel_hi:[1,0]
	v_pk_mul_f32 v[40:41], v[40:41], v[240:241] op_sel_hi:[1,0]
	v_pk_mul_f32 v[42:43], v[42:43], v[240:241] op_sel_hi:[1,0]
	v_pk_mul_f32 v[44:45], v[44:45], v[240:241] op_sel_hi:[1,0]
	v_pk_mul_f32 v[46:47], v[46:47], v[240:241] op_sel_hi:[1,0]
	v_pk_mul_f32 v[16:17], v[16:17], v[240:241] op_sel_hi:[1,0]
	v_pk_mul_f32 v[18:19], v[18:19], v[240:241] op_sel_hi:[1,0]
	v_pk_mul_f32 v[20:21], v[20:21], v[240:241] op_sel_hi:[1,0]
	v_pk_mul_f32 v[22:23], v[22:23], v[240:241] op_sel_hi:[1,0]
	v_pk_mul_f32 v[24:25], v[24:25], v[240:241] op_sel_hi:[1,0]
	v_pk_mul_f32 v[26:27], v[26:27], v[240:241] op_sel_hi:[1,0]
	v_pk_mul_f32 v[28:29], v[28:29], v[240:241] op_sel_hi:[1,0]
	v_pk_mul_f32 v[30:31], v[30:31], v[240:241] op_sel_hi:[1,0]
	s_branch .Latt_diffT_norescale
